# cache_conv (cached K/V conversion, independent of X) moved from the even layers' first norm phase into the idle tail of the following abin GEMM phase (WGs 64-255)
# speedup vs baseline: 1.0096x; 1.0096x over previous
.LBB0_931:
	s_cmp_lt_u32 s2, 64
	s_cbranch_scc1 .Lcc_skip
	v_writelane_b32 v255, s2, 62
	v_writelane_b32 v255, s34, 63
	s_sub_i32 s2, s2, 64
	s_sub_i32 s34, s34, 64
	s_branch .Lcc_entry
.Lcc_ret:
	v_readlane_b32 s2, v255, 62
	v_readlane_b32 s34, v255, 63

.LBB0_979:
	s_or_b64 exec, exec, s[0:1]
	s_branch .LBB0_1015
.Lcc_entry:
	s_mov_b32 s0, s2
	v_mov_b32_e32 v0, v196
	s_lshl_b32 s0, s0, 9
	v_readfirstlane_b32 s1, v0
	s_and_b32 s1, s1, 0xffffff00
	s_add_i32 s0, s1, s0
	v_mov_b32_e32 v6, v196
	v_readlane_b32 s40, v255, 12
	s_mov_b32 s1, 0x80000
	v_or_b32_sdwa v2, s0, v6 dst_sel:DWORD dst_unused:UNUSED_PAD src0_sel:DWORD src1_sel:BYTE_0
	s_mov_b32 s27, 0x7ffff
	v_readlane_b32 s44, v255, 16
	v_readlane_b32 s45, v255, 17
	v_readlane_b32 s46, v255, 18
	v_readlane_b32 s47, v255, 19
	s_mov_b32 s25, s34
	v_cmp_gt_i32_e32 vcc, s1, v2
	v_readlane_b32 s41, v255, 13
	v_readlane_b32 s42, v255, 14
	v_readlane_b32 s43, v255, 15
	s_and_saveexec_b64 s[28:29], vcc
	s_cbranch_execz .LBB0_1014
	s_lshl_b32 s24, s25, 9
	v_cvt_f32_u32_e32 v0, s24
	s_add_i32 s0, s0, s24
	v_or_b32_sdwa v3, s0, v6 dst_sel:DWORD dst_unused:UNUSED_PAD src0_sel:DWORD src1_sel:BYTE_0
	s_mov_b32 s0, 0x80000
	v_rcp_iflag_f32_e32 v0, v0
	s_sub_i32 s1, 0, s24
	v_max_i32_e32 v4, 0x80000, v3
	v_cmp_gt_i32_e32 vcc, s0, v3
	v_mul_f32_e32 v0, 0x4f7ffffe, v0
	v_cvt_u32_f32_e32 v0, v0
	v_cndmask_b32_e64 v5, 1, 2, vcc
	v_subb_co_u32_e32 v3, vcc, v4, v3, vcc
	v_mul_lo_u32 v4, s1, v0
	v_mul_hi_u32 v4, v0, v4
	s_waitcnt vmcnt(1)
	v_add_u32_e32 v8, v0, v4
	v_mul_hi_u32 v0, v3, v8
	v_mul_lo_u32 v4, v0, s24
	v_sub_u32_e32 v3, v3, v4
	v_add_u32_e32 v7, 1, v0
	v_cmp_le_u32_e32 vcc, s24, v3
	v_subrev_u32_e32 v4, s24, v3
	s_mov_b64 s[20:21], -1
	v_cndmask_b32_e32 v0, v0, v7, vcc
	v_cndmask_b32_e32 v3, v3, v4, vcc
	v_add_u32_e32 v4, 1, v0
	v_cmp_le_u32_e32 vcc, s24, v3
	v_add_u32_e32 v3, s24, v2
	s_nop 0
	v_cndmask_b32_e32 v0, v0, v4, vcc
	v_add_u32_e32 v9, v5, v0
	v_add_u32_e32 v7, -2, v9
	v_cmp_lt_u32_e32 vcc, 1, v9
	v_lshrrev_b32_e32 v11, 1, v7
	v_mov_b32_e32 v4, v2
	s_and_saveexec_b64 s[0:1], vcc
	s_cbranch_execz .LBB0_989
	s_lshl_b32 s26, s25, 10
	v_add_u32_e32 v10, 1, v11
	v_cmp_lt_u32_e64 s[40:41], 5, v7
	v_mov_b64_e32 v[4:5], v[2:3]
	s_and_saveexec_b64 s[20:21], s[40:41]
	s_cbranch_execz .LBB0_985
	v_readlane_b32 s4, v253, 46
	v_and_b32_e32 v12, -4, v10
	s_mov_b64 s[22:23], 0
	v_mov_b64_e32 v[4:5], v[2:3]
	v_readlane_b32 s6, v253, 48
	v_readlane_b32 s7, v253, 49
	v_readlane_b32 s5, v253, 47
	v_readlane_b32 s8, v253, 50
	v_readlane_b32 s9, v253, 51
	v_readlane_b32 s10, v253, 52
	v_readlane_b32 s11, v253, 53
	v_readlane_b32 s12, v253, 54
	v_readlane_b32 s13, v253, 55
	v_readlane_b32 s14, v253, 56
	v_readlane_b32 s15, v253, 57
	v_readlane_b32 s16, v253, 58
	v_readlane_b32 s17, v253, 59
	v_readlane_b32 s18, v253, 60
	v_readlane_b32 s19, v253, 61

.LBB0_1014:
	s_or_b64 exec, exec, s[28:29]
	s_branch .Lcc_ret
